# v33 + oddmix conv loop head: 14 serialized ds_read_u16 (wait after each pair) batched into their final registers, shifts after one counted wait; bit-identical
# speedup vs baseline: 1.0045x; 1.0032x over previous
; #define LAS __attribute__((address_space(3)))
; __device__ __forceinline__ void oddmix_phase(const Args& a, int li, LAS unsigned char* lds) {
;     ...
;         for (int ob = 0; ob < 4; ++ob) { float xin[38];
; #pragma unroll
;             for (int i = 0; i < 38; ++i) xin[i] = bf1(*(const LAS bf16*)(lds + OM_GL + (ob * 8 + i) * 1024 + tid * 2));
; #pragma unroll
;             for (int t = 0; t < 8; ++t) { float acc = cb;
; #pragma unroll
;                 for (int k = 0; k < 31; ++k) acc += cw[k] * xin[t + k];
;                 *(LAS float*)(lds + OM_CV + (ob * 8 + t) * 2048 + tid * 4) = acc; } }
.LBB0_293:
	v_lshl_add_u32 v168, s1, 13, v147
	v_lshl_add_u32 v170, s0, 13, v147
	ds_read_u16 v202, v168
	ds_read_u16 v203, v170
	v_lshl_add_u32 v173, s0, 14, v204
	v_add_u32_e32 v178, 0xf800, v173
	s_add_i32 s0, s0, 2
	ds_read_u16 v200, v168 offset:1024
	ds_read_u16 v201, v170 offset:1024
	s_add_i32 s2, s2, -2
	ds_read_u16 v198, v168 offset:2048
	ds_read_u16 v199, v170 offset:2048
	ds_read_u16 v196, v168 offset:3072
	ds_read_u16 v197, v170 offset:3072
	ds_read_u16 v192, v168 offset:4096
	ds_read_u16 v193, v170 offset:4096
	ds_read_u16 v58, v168 offset:5120
	ds_read_u16 v59, v170 offset:5120
	ds_read_u16 v36, v168 offset:6144
	ds_read_u16 v37, v170 offset:6144
	ds_read_u16 v16, v168 offset:7168
	ds_read_u16 v17, v170 offset:7168
	ds_read_u16 v18, v168 offset:8192
	ds_read_u16 v19, v170 offset:8192
	ds_read_u16 v20, v168 offset:9216
	ds_read_u16 v21, v170 offset:9216
	ds_read_u16 v22, v168 offset:10240
	ds_read_u16 v23, v170 offset:10240
	ds_read_u16 v24, v168 offset:11264
	ds_read_u16 v25, v170 offset:11264
	ds_read_u16 v26, v168 offset:12288
	ds_read_u16 v27, v170 offset:12288
	ds_read_u16 v28, v168 offset:13312
	ds_read_u16 v29, v170 offset:13312
	ds_read_u16 v30, v168 offset:14336
	ds_read_u16 v31, v170 offset:14336
	ds_read_u16 v32, v168 offset:15360
	ds_read_u16 v33, v170 offset:15360
	ds_read_u16 v34, v168 offset:16384
	ds_read_u16 v35, v170 offset:16384
	ds_read_u16 v38, v168 offset:17408
	ds_read_u16 v39, v170 offset:17408
	ds_read_u16 v40, v168 offset:18432
	ds_read_u16 v41, v170 offset:18432
	ds_read_u16 v42, v168 offset:19456
	ds_read_u16 v43, v170 offset:19456
	ds_read_u16 v44, v168 offset:20480
	ds_read_u16 v45, v170 offset:20480
	ds_read_u16 v46, v168 offset:21504
	ds_read_u16 v47, v170 offset:21504
	ds_read_u16 v48, v168 offset:22528
	ds_read_u16 v49, v170 offset:22528
	ds_read_u16 v50, v168 offset:23552
	ds_read_u16 v51, v170 offset:23552
	ds_read_u16 v52, v168 offset:24576
	ds_read_u16 v53, v170 offset:24576
	ds_read_u16 v54, v168 offset:25600
	ds_read_u16 v55, v170 offset:25600
	ds_read_u16 v56, v168 offset:26624
	ds_read_u16 v57, v170 offset:26624
	ds_read_u16 v60, v168 offset:27648
	ds_read_u16 v61, v170 offset:27648
	ds_read_u16 v62, v168 offset:28672
	ds_read_u16 v63, v170 offset:28672
	ds_read_u16 v64, v168 offset:29696
	ds_read_u16 v65, v170 offset:29696
	ds_read_u16 v66, v168 offset:30720
	ds_read_u16 v67, v170 offset:30720
	ds_read_u16 v68, v168 offset:31744
	ds_read_u16 v69, v170 offset:31744
	ds_read_u16 v70, v168 offset:32768
	ds_read_u16 v71, v170 offset:32768
	ds_read_u16 v72, v168 offset:33792
	ds_read_u16 v73, v170 offset:33792
	ds_read_u16 v74, v168 offset:34816
	ds_read_u16 v75, v170 offset:34816
	ds_read_u16 v76, v168 offset:35840
	ds_read_u16 v77, v170 offset:35840
	ds_read_u16 v78, v168 offset:36864
	ds_read_u16 v79, v170 offset:36864
	ds_read_u16 v168, v168 offset:37888
	ds_read_u16 v170, v170 offset:37888
	s_waitcnt lgkmcnt(14)
	v_lshlrev_b32_e32 v202, 16, v202
	v_lshlrev_b32_e32 v203, 16, v203
	v_lshlrev_b32_e32 v200, 16, v200
	v_lshlrev_b32_e32 v201, 16, v201
	v_lshlrev_b32_e32 v198, 16, v198
	v_lshlrev_b32_e32 v199, 16, v199
	v_lshlrev_b32_e32 v196, 16, v196
	v_lshlrev_b32_e32 v197, 16, v197
	v_lshlrev_b32_e32 v192, 16, v192
	v_lshlrev_b32_e32 v193, 16, v193
	v_lshlrev_b32_e32 v58, 16, v58
	v_lshlrev_b32_e32 v59, 16, v59
	v_lshlrev_b32_e32 v36, 16, v36
	v_lshlrev_b32_e32 v37, 16, v37
	v_lshlrev_b32_e32 v17, 16, v17
	v_lshlrev_b32_e32 v16, 16, v16
	v_lshlrev_b32_e32 v19, 16, v19
	v_lshlrev_b32_e32 v18, 16, v18
	s_waitcnt lgkmcnt(0)
	v_lshlrev_b32_e32 v195, 16, v170
	v_pk_fma_f32 v[170:171], v[114:115], v[202:203], v[130:131]
	v_lshlrev_b32_e32 v21, 16, v21
	v_pk_fma_f32 v[170:171], v[116:117], v[200:201], v[170:171]
	v_lshlrev_b32_e32 v20, 16, v20
	v_pk_fma_f32 v[170:171], v[82:83], v[198:199], v[170:171]
	v_lshlrev_b32_e32 v23, 16, v23
	v_pk_fma_f32 v[170:171], v[118:119], v[196:197], v[170:171]
	v_lshlrev_b32_e32 v22, 16, v22
	v_pk_fma_f32 v[170:171], v[84:85], v[192:193], v[170:171]
	v_lshlrev_b32_e32 v25, 16, v25
	v_pk_fma_f32 v[170:171], v[86:87], v[58:59], v[170:171]
	v_lshlrev_b32_e32 v24, 16, v24
	v_pk_fma_f32 v[170:171], v[88:89], v[36:37], v[170:171]
	v_lshlrev_b32_e32 v27, 16, v27
	v_pk_fma_f32 v[170:171], v[120:121], v[16:17], v[170:171]
	v_lshlrev_b32_e32 v26, 16, v26
	v_pk_fma_f32 v[170:171], v[90:91], v[18:19], v[170:171]
	v_lshlrev_b32_e32 v29, 16, v29
	v_pk_fma_f32 v[170:171], v[92:93], v[20:21], v[170:171]
	v_lshlrev_b32_e32 v28, 16, v28
	v_pk_fma_f32 v[170:171], v[94:95], v[22:23], v[170:171]
	v_lshlrev_b32_e32 v31, 16, v31
	v_pk_fma_f32 v[170:171], v[122:123], v[24:25], v[170:171]
	v_lshlrev_b32_e32 v30, 16, v30
	v_pk_fma_f32 v[170:171], v[96:97], v[26:27], v[170:171]
	v_lshlrev_b32_e32 v33, 16, v33
	v_pk_fma_f32 v[170:171], v[98:99], v[28:29], v[170:171]
	v_lshlrev_b32_e32 v32, 16, v32
	v_pk_fma_f32 v[170:171], v[100:101], v[30:31], v[170:171]
	v_lshlrev_b32_e32 v35, 16, v35
	v_lshlrev_b32_e32 v34, 16, v34
	v_pk_fma_f32 v[170:171], v[124:125], v[32:33], v[170:171]
	v_lshlrev_b32_e32 v39, 16, v39
	v_lshlrev_b32_e32 v38, 16, v38
	v_pk_fma_f32 v[170:171], v[102:103], v[34:35], v[170:171]
	v_lshlrev_b32_e32 v41, 16, v41
	v_lshlrev_b32_e32 v40, 16, v40
	v_pk_fma_f32 v[170:171], v[104:105], v[38:39], v[170:171]
	v_lshlrev_b32_e32 v43, 16, v43
	v_lshlrev_b32_e32 v42, 16, v42
	v_pk_fma_f32 v[170:171], v[106:107], v[40:41], v[170:171]
	v_lshlrev_b32_e32 v45, 16, v45
	v_lshlrev_b32_e32 v44, 16, v44
	v_pk_fma_f32 v[170:171], v[126:127], v[42:43], v[170:171]
	v_lshlrev_b32_e32 v47, 16, v47
	v_lshlrev_b32_e32 v46, 16, v46
	v_pk_fma_f32 v[170:171], v[108:109], v[44:45], v[170:171]
; #define LAS __attribute__((address_space(3)))
; __device__ __forceinline__ void oddmix_phase(const Args& a, int li, LAS unsigned char* lds) {
;     ...
;             for (int t = 0; t < 8; ++t) { float acc = cb;
; #pragma unroll
;                 for (int k = 0; k < 31; ++k) acc += cw[k] * xin[t + k];
;                 *(LAS float*)(lds + OM_CV + (ob * 8 + t) * 2048 + tid * 4) = acc; } }
	v_lshlrev_b32_e32 v49, 16, v49
	v_lshlrev_b32_e32 v48, 16, v48
	v_pk_fma_f32 v[170:171], v[110:111], v[46:47], v[170:171]
	v_lshlrev_b32_e32 v51, 16, v51
	v_lshlrev_b32_e32 v50, 16, v50
	v_pk_fma_f32 v[170:171], v[112:113], v[48:49], v[170:171]
	v_lshlrev_b32_e32 v53, 16, v53
	v_lshlrev_b32_e32 v52, 16, v52
	v_pk_fma_f32 v[170:171], v[128:129], v[50:51], v[170:171]
	v_lshlrev_b32_e32 v55, 16, v55
	v_lshlrev_b32_e32 v54, 16, v54
	v_pk_fma_f32 v[170:171], v[132:133], v[52:53], v[170:171]
	v_lshlrev_b32_e32 v57, 16, v57
	v_lshlrev_b32_e32 v56, 16, v56
	v_pk_fma_f32 v[170:171], v[134:135], v[54:55], v[170:171]
	v_lshlrev_b32_e32 v61, 16, v61
	v_lshlrev_b32_e32 v60, 16, v60
	v_pk_fma_f32 v[170:171], v[136:137], v[56:57], v[170:171]
	v_lshlrev_b32_e32 v63, 16, v63
	v_lshlrev_b32_e32 v62, 16, v62
	v_pk_fma_f32 v[170:171], v[142:143], v[60:61], v[170:171]
	v_lshlrev_b32_e32 v65, 16, v65
	v_lshlrev_b32_e32 v64, 16, v64
	v_pk_fma_f32 v[170:171], v[138:139], v[62:63], v[170:171]
	v_lshlrev_b32_e32 v67, 16, v67
	v_lshlrev_b32_e32 v66, 16, v66
	v_pk_fma_f32 v[170:171], v[140:141], v[64:65], v[170:171]
	v_lshlrev_b32_e32 v194, 16, v168
	v_lshl_add_u32 v168, s1, 14, v204
	v_pk_fma_f32 v[170:171], v[144:145], v[66:67], v[170:171]
	ds_write_b32 v168, v170 offset:63488
	ds_write_b32 v173, v171 offset:63488
	v_pk_fma_f32 v[170:171], v[114:115], v[200:201], v[130:131]
	v_lshlrev_b32_e32 v69, 16, v69
	v_pk_fma_f32 v[170:171], v[116:117], v[198:199], v[170:171]
	v_lshlrev_b32_e32 v68, 16, v68
	v_pk_fma_f32 v[170:171], v[82:83], v[196:197], v[170:171]
	v_add_u32_e32 v172, 0xf800, v168
	v_pk_fma_f32 v[170:171], v[118:119], v[192:193], v[170:171]
	v_lshlrev_b32_e32 v71, 16, v71
	v_pk_fma_f32 v[170:171], v[84:85], v[58:59], v[170:171]
	v_lshlrev_b32_e32 v70, 16, v70
	v_pk_fma_f32 v[170:171], v[86:87], v[36:37], v[170:171]
	v_lshlrev_b32_e32 v73, 16, v73
	v_pk_fma_f32 v[170:171], v[88:89], v[16:17], v[170:171]
	v_lshlrev_b32_e32 v72, 16, v72
	v_pk_fma_f32 v[170:171], v[120:121], v[18:19], v[170:171]
	v_lshlrev_b32_e32 v75, 16, v75
	v_pk_fma_f32 v[170:171], v[90:91], v[20:21], v[170:171]
	v_lshlrev_b32_e32 v74, 16, v74
	v_pk_fma_f32 v[170:171], v[92:93], v[22:23], v[170:171]
	v_lshlrev_b32_e32 v77, 16, v77
	v_pk_fma_f32 v[170:171], v[94:95], v[24:25], v[170:171]
	v_lshlrev_b32_e32 v76, 16, v76
	v_pk_fma_f32 v[170:171], v[122:123], v[26:27], v[170:171]
	v_lshlrev_b32_e32 v79, 16, v79
	v_pk_fma_f32 v[170:171], v[96:97], v[28:29], v[170:171]
	v_lshlrev_b32_e32 v78, 16, v78
	v_pk_fma_f32 v[170:171], v[98:99], v[30:31], v[170:171]
	s_add_i32 s1, s1, 2
	v_pk_fma_f32 v[170:171], v[100:101], v[32:33], v[170:171]
	s_cmp_lg_u32 s2, 0
	v_pk_fma_f32 v[170:171], v[124:125], v[34:35], v[170:171]
	s_nop 0
	v_pk_fma_f32 v[170:171], v[102:103], v[38:39], v[170:171]
	s_nop 0
	v_pk_fma_f32 v[170:171], v[104:105], v[40:41], v[170:171]
	s_nop 0
	v_pk_fma_f32 v[170:171], v[106:107], v[42:43], v[170:171]
	s_nop 0
	v_pk_fma_f32 v[170:171], v[126:127], v[44:45], v[170:171]
	s_nop 0
	v_pk_fma_f32 v[170:171], v[108:109], v[46:47], v[170:171]
	s_nop 0
	v_pk_fma_f32 v[170:171], v[110:111], v[48:49], v[170:171]
	s_nop 0
	v_pk_fma_f32 v[170:171], v[112:113], v[50:51], v[170:171]
	s_nop 0
	v_pk_fma_f32 v[170:171], v[128:129], v[52:53], v[170:171]
	s_nop 0
	v_pk_fma_f32 v[170:171], v[132:133], v[54:55], v[170:171]
	s_nop 0
	v_pk_fma_f32 v[170:171], v[134:135], v[56:57], v[170:171]
	s_nop 0
	v_pk_fma_f32 v[170:171], v[136:137], v[60:61], v[170:171]
	s_nop 0
	v_pk_fma_f32 v[170:171], v[142:143], v[62:63], v[170:171]
	s_nop 0
	v_pk_fma_f32 v[170:171], v[138:139], v[64:65], v[170:171]
	s_nop 0
	v_pk_fma_f32 v[170:171], v[140:141], v[66:67], v[170:171]
	s_nop 0
	v_pk_fma_f32 v[170:171], v[144:145], v[68:69], v[170:171]
	ds_write_b32 v172, v170 offset:2048
	ds_write_b32 v178, v171 offset:2048
	v_pk_fma_f32 v[170:171], v[114:115], v[198:199], v[130:131]
	s_nop 0
	v_pk_fma_f32 v[170:171], v[116:117], v[196:197], v[170:171]
	s_nop 0
	v_pk_fma_f32 v[170:171], v[82:83], v[192:193], v[170:171]
	s_nop 0
	v_pk_fma_f32 v[170:171], v[118:119], v[58:59], v[170:171]
	s_nop 0
	v_pk_fma_f32 v[170:171], v[84:85], v[36:37], v[170:171]
	s_nop 0
	v_pk_fma_f32 v[170:171], v[86:87], v[16:17], v[170:171]
	s_nop 0
	v_pk_fma_f32 v[170:171], v[88:89], v[18:19], v[170:171]
	s_nop 0
	v_pk_fma_f32 v[170:171], v[120:121], v[20:21], v[170:171]
	s_nop 0
	v_pk_fma_f32 v[170:171], v[90:91], v[22:23], v[170:171]
	s_nop 0
	v_pk_fma_f32 v[170:171], v[92:93], v[24:25], v[170:171]
	s_nop 0
	v_pk_fma_f32 v[170:171], v[94:95], v[26:27], v[170:171]
	s_nop 0
	v_pk_fma_f32 v[170:171], v[122:123], v[28:29], v[170:171]
	s_nop 0
	v_pk_fma_f32 v[170:171], v[96:97], v[30:31], v[170:171]
	s_nop 0
	v_pk_fma_f32 v[170:171], v[98:99], v[32:33], v[170:171]
	s_nop 0
	v_pk_fma_f32 v[170:171], v[100:101], v[34:35], v[170:171]
	s_nop 0
	v_pk_fma_f32 v[170:171], v[124:125], v[38:39], v[170:171]
	s_nop 0
	v_pk_fma_f32 v[170:171], v[102:103], v[40:41], v[170:171]
	s_nop 0
	v_pk_fma_f32 v[170:171], v[104:105], v[42:43], v[170:171]
	s_nop 0
	v_pk_fma_f32 v[170:171], v[106:107], v[44:45], v[170:171]
	s_nop 0
	v_pk_fma_f32 v[170:171], v[126:127], v[46:47], v[170:171]
	s_nop 0
	v_pk_fma_f32 v[170:171], v[108:109], v[48:49], v[170:171]
	s_nop 0
	v_pk_fma_f32 v[170:171], v[110:111], v[50:51], v[170:171]
	s_nop 0
	v_pk_fma_f32 v[170:171], v[112:113], v[52:53], v[170:171]
	s_nop 0
	v_pk_fma_f32 v[170:171], v[128:129], v[54:55], v[170:171]
	s_nop 0
	v_pk_fma_f32 v[170:171], v[132:133], v[56:57], v[170:171]
	s_nop 0
	v_pk_fma_f32 v[170:171], v[134:135], v[60:61], v[170:171]
	s_nop 0
	v_pk_fma_f32 v[170:171], v[136:137], v[62:63], v[170:171]
	s_nop 0
; #define LAS __attribute__((address_space(3)))
; __device__ __forceinline__ void oddmix_phase(const Args& a, int li, LAS unsigned char* lds) {
;     ...
;             for (int t = 0; t < 8; ++t) { float acc = cb;
; #pragma unroll
;                 for (int k = 0; k < 31; ++k) acc += cw[k] * xin[t + k];
;                 *(LAS float*)(lds + OM_CV + (ob * 8 + t) * 2048 + tid * 4) = acc; } }
	v_pk_fma_f32 v[170:171], v[142:143], v[64:65], v[170:171]
	s_nop 0
	v_pk_fma_f32 v[170:171], v[138:139], v[66:67], v[170:171]
	s_nop 0
	v_pk_fma_f32 v[170:171], v[140:141], v[68:69], v[170:171]
	s_nop 0
	v_pk_fma_f32 v[170:171], v[144:145], v[70:71], v[170:171]
	ds_write_b32 v172, v170 offset:4096
	ds_write_b32 v178, v171 offset:4096
	v_pk_fma_f32 v[170:171], v[114:115], v[196:197], v[130:131]
	s_nop 0
	v_pk_fma_f32 v[170:171], v[116:117], v[192:193], v[170:171]
	s_nop 0
	v_pk_fma_f32 v[170:171], v[82:83], v[58:59], v[170:171]
	s_nop 0
	v_pk_fma_f32 v[170:171], v[118:119], v[36:37], v[170:171]
	s_nop 0
	v_pk_fma_f32 v[170:171], v[84:85], v[16:17], v[170:171]
	s_nop 0
	v_pk_fma_f32 v[170:171], v[86:87], v[18:19], v[170:171]
	s_nop 0
	v_pk_fma_f32 v[170:171], v[88:89], v[20:21], v[170:171]
	s_nop 0
	v_pk_fma_f32 v[170:171], v[120:121], v[22:23], v[170:171]
	s_nop 0
	v_pk_fma_f32 v[170:171], v[90:91], v[24:25], v[170:171]
	s_nop 0
	v_pk_fma_f32 v[170:171], v[92:93], v[26:27], v[170:171]
	s_nop 0
	v_pk_fma_f32 v[170:171], v[94:95], v[28:29], v[170:171]
	s_nop 0
	v_pk_fma_f32 v[170:171], v[122:123], v[30:31], v[170:171]
	s_nop 0
	v_pk_fma_f32 v[170:171], v[96:97], v[32:33], v[170:171]
	s_nop 0
	v_pk_fma_f32 v[170:171], v[98:99], v[34:35], v[170:171]
	s_nop 0
	v_pk_fma_f32 v[170:171], v[100:101], v[38:39], v[170:171]
	s_nop 0
	v_pk_fma_f32 v[170:171], v[124:125], v[40:41], v[170:171]
	s_nop 0
	v_pk_fma_f32 v[170:171], v[102:103], v[42:43], v[170:171]
	s_nop 0
	v_pk_fma_f32 v[170:171], v[104:105], v[44:45], v[170:171]
	s_nop 0
	v_pk_fma_f32 v[170:171], v[106:107], v[46:47], v[170:171]
	s_nop 0
	v_pk_fma_f32 v[170:171], v[126:127], v[48:49], v[170:171]
	s_nop 0
	v_pk_fma_f32 v[170:171], v[108:109], v[50:51], v[170:171]
	s_nop 0
	v_pk_fma_f32 v[170:171], v[110:111], v[52:53], v[170:171]
	s_nop 0
	v_pk_fma_f32 v[170:171], v[112:113], v[54:55], v[170:171]
	s_nop 0
	v_pk_fma_f32 v[170:171], v[128:129], v[56:57], v[170:171]
	s_nop 0
	v_pk_fma_f32 v[170:171], v[132:133], v[60:61], v[170:171]
	s_nop 0
	v_pk_fma_f32 v[170:171], v[134:135], v[62:63], v[170:171]
	s_nop 0
	v_pk_fma_f32 v[170:171], v[136:137], v[64:65], v[170:171]
	s_nop 0
	v_pk_fma_f32 v[170:171], v[142:143], v[66:67], v[170:171]
	s_nop 0
	v_pk_fma_f32 v[170:171], v[138:139], v[68:69], v[170:171]
	s_nop 0
	v_pk_fma_f32 v[170:171], v[140:141], v[70:71], v[170:171]
	s_nop 0
	v_pk_fma_f32 v[170:171], v[144:145], v[72:73], v[170:171]
	ds_write_b32 v172, v170 offset:6144
	ds_write_b32 v178, v171 offset:6144
	v_pk_fma_f32 v[170:171], v[114:115], v[192:193], v[130:131]
	s_nop 0
	v_pk_fma_f32 v[170:171], v[116:117], v[58:59], v[170:171]
	v_pk_fma_f32 v[58:59], v[114:115], v[58:59], v[130:131]
	v_pk_fma_f32 v[170:171], v[82:83], v[36:37], v[170:171]
	v_pk_fma_f32 v[58:59], v[116:117], v[36:37], v[58:59]
	v_pk_fma_f32 v[36:37], v[114:115], v[36:37], v[130:131]
	v_pk_fma_f32 v[170:171], v[118:119], v[16:17], v[170:171]
	v_pk_fma_f32 v[58:59], v[82:83], v[16:17], v[58:59]
	v_pk_fma_f32 v[36:37], v[116:117], v[16:17], v[36:37]
	v_pk_fma_f32 v[16:17], v[114:115], v[16:17], v[130:131]
	v_pk_fma_f32 v[36:37], v[82:83], v[18:19], v[36:37]
	v_pk_fma_f32 v[16:17], v[116:117], v[18:19], v[16:17]
	v_pk_fma_f32 v[58:59], v[118:119], v[18:19], v[58:59]
	v_pk_fma_f32 v[16:17], v[82:83], v[20:21], v[16:17]
	v_pk_fma_f32 v[36:37], v[118:119], v[20:21], v[36:37]
	v_pk_fma_f32 v[16:17], v[118:119], v[22:23], v[16:17]
	v_pk_fma_f32 v[170:171], v[84:85], v[18:19], v[170:171]
	v_pk_fma_f32 v[58:59], v[84:85], v[20:21], v[58:59]
	v_pk_fma_f32 v[36:37], v[84:85], v[22:23], v[36:37]
	v_pk_fma_f32 v[16:17], v[84:85], v[24:25], v[16:17]
	v_pk_fma_f32 v[170:171], v[86:87], v[20:21], v[170:171]
	v_pk_fma_f32 v[58:59], v[86:87], v[22:23], v[58:59]
	v_pk_fma_f32 v[36:37], v[86:87], v[24:25], v[36:37]
	v_pk_fma_f32 v[16:17], v[86:87], v[26:27], v[16:17]
	v_pk_fma_f32 v[170:171], v[88:89], v[22:23], v[170:171]
	v_pk_fma_f32 v[58:59], v[88:89], v[24:25], v[58:59]
	v_pk_fma_f32 v[36:37], v[88:89], v[26:27], v[36:37]
	v_pk_fma_f32 v[16:17], v[88:89], v[28:29], v[16:17]
	v_pk_fma_f32 v[170:171], v[120:121], v[24:25], v[170:171]
	v_pk_fma_f32 v[58:59], v[120:121], v[26:27], v[58:59]
	v_pk_fma_f32 v[36:37], v[120:121], v[28:29], v[36:37]
	v_pk_fma_f32 v[16:17], v[120:121], v[30:31], v[16:17]
	v_pk_fma_f32 v[170:171], v[90:91], v[26:27], v[170:171]
	v_pk_fma_f32 v[58:59], v[90:91], v[28:29], v[58:59]
	v_pk_fma_f32 v[36:37], v[90:91], v[30:31], v[36:37]
	v_pk_fma_f32 v[16:17], v[90:91], v[32:33], v[16:17]
	v_pk_fma_f32 v[170:171], v[92:93], v[28:29], v[170:171]
	v_pk_fma_f32 v[58:59], v[92:93], v[30:31], v[58:59]
	v_pk_fma_f32 v[36:37], v[92:93], v[32:33], v[36:37]
	v_pk_fma_f32 v[16:17], v[92:93], v[34:35], v[16:17]
	v_pk_fma_f32 v[170:171], v[94:95], v[30:31], v[170:171]
	v_pk_fma_f32 v[58:59], v[94:95], v[32:33], v[58:59]
	v_pk_fma_f32 v[36:37], v[94:95], v[34:35], v[36:37]
	v_pk_fma_f32 v[16:17], v[94:95], v[38:39], v[16:17]
; #define LAS __attribute__((address_space(3)))
; __device__ __forceinline__ void oddmix_phase(const Args& a, int li, LAS unsigned char* lds) {
;     ...
;             for (int t = 0; t < 8; ++t) { float acc = cb;
; #pragma unroll
;                 for (int k = 0; k < 31; ++k) acc += cw[k] * xin[t + k];
;                 *(LAS float*)(lds + OM_CV + (ob * 8 + t) * 2048 + tid * 4) = acc; } }
;         __syncthreads();
; #pragma unroll 1
;         for (int r = 0; r < 4; ++r) { const int t = wave * 4 + r; f32x4 v0 = *(const LAS f32x4*)(lds + OM_CV + t * 2048 + lane * 32), v1 = *(const LAS f32x4*)(lds + OM_CV + t * 2048 + lane * 32 + 16);
	v_pk_fma_f32 v[170:171], v[122:123], v[32:33], v[170:171]
	v_pk_fma_f32 v[58:59], v[122:123], v[34:35], v[58:59]
	v_pk_fma_f32 v[36:37], v[122:123], v[38:39], v[36:37]
	v_pk_fma_f32 v[16:17], v[122:123], v[40:41], v[16:17]
	v_pk_fma_f32 v[170:171], v[96:97], v[34:35], v[170:171]
	v_pk_fma_f32 v[58:59], v[96:97], v[38:39], v[58:59]
	v_pk_fma_f32 v[36:37], v[96:97], v[40:41], v[36:37]
	v_pk_fma_f32 v[16:17], v[96:97], v[42:43], v[16:17]
	v_pk_fma_f32 v[170:171], v[98:99], v[38:39], v[170:171]
	v_pk_fma_f32 v[58:59], v[98:99], v[40:41], v[58:59]
	v_pk_fma_f32 v[36:37], v[98:99], v[42:43], v[36:37]
	v_pk_fma_f32 v[16:17], v[98:99], v[44:45], v[16:17]
	v_pk_fma_f32 v[170:171], v[100:101], v[40:41], v[170:171]
	v_pk_fma_f32 v[58:59], v[100:101], v[42:43], v[58:59]
	v_pk_fma_f32 v[36:37], v[100:101], v[44:45], v[36:37]
	v_pk_fma_f32 v[16:17], v[100:101], v[46:47], v[16:17]
	v_pk_fma_f32 v[170:171], v[124:125], v[42:43], v[170:171]
	v_pk_fma_f32 v[58:59], v[124:125], v[44:45], v[58:59]
	v_pk_fma_f32 v[36:37], v[124:125], v[46:47], v[36:37]
	v_pk_fma_f32 v[16:17], v[124:125], v[48:49], v[16:17]
	v_pk_fma_f32 v[170:171], v[102:103], v[44:45], v[170:171]
	v_pk_fma_f32 v[58:59], v[102:103], v[46:47], v[58:59]
	v_pk_fma_f32 v[36:37], v[102:103], v[48:49], v[36:37]
	v_pk_fma_f32 v[16:17], v[102:103], v[50:51], v[16:17]
	v_pk_fma_f32 v[170:171], v[104:105], v[46:47], v[170:171]
	v_pk_fma_f32 v[58:59], v[104:105], v[48:49], v[58:59]
	v_pk_fma_f32 v[36:37], v[104:105], v[50:51], v[36:37]
	v_pk_fma_f32 v[16:17], v[104:105], v[52:53], v[16:17]
	v_pk_fma_f32 v[170:171], v[106:107], v[48:49], v[170:171]
	v_pk_fma_f32 v[58:59], v[106:107], v[50:51], v[58:59]
	v_pk_fma_f32 v[36:37], v[106:107], v[52:53], v[36:37]
	v_pk_fma_f32 v[16:17], v[106:107], v[54:55], v[16:17]
	v_pk_fma_f32 v[170:171], v[126:127], v[50:51], v[170:171]
	v_pk_fma_f32 v[58:59], v[126:127], v[52:53], v[58:59]
	v_pk_fma_f32 v[36:37], v[126:127], v[54:55], v[36:37]
	v_pk_fma_f32 v[16:17], v[126:127], v[56:57], v[16:17]
	v_pk_fma_f32 v[170:171], v[108:109], v[52:53], v[170:171]
	v_pk_fma_f32 v[58:59], v[108:109], v[54:55], v[58:59]
	v_pk_fma_f32 v[36:37], v[108:109], v[56:57], v[36:37]
	v_pk_fma_f32 v[16:17], v[108:109], v[60:61], v[16:17]
	v_pk_fma_f32 v[170:171], v[110:111], v[54:55], v[170:171]
	v_pk_fma_f32 v[58:59], v[110:111], v[56:57], v[58:59]
	v_pk_fma_f32 v[36:37], v[110:111], v[60:61], v[36:37]
	v_pk_fma_f32 v[16:17], v[110:111], v[62:63], v[16:17]
	v_pk_fma_f32 v[170:171], v[112:113], v[56:57], v[170:171]
	v_pk_fma_f32 v[58:59], v[112:113], v[60:61], v[58:59]
	v_pk_fma_f32 v[36:37], v[112:113], v[62:63], v[36:37]
	v_pk_fma_f32 v[16:17], v[112:113], v[64:65], v[16:17]
	v_pk_fma_f32 v[170:171], v[128:129], v[60:61], v[170:171]
	v_pk_fma_f32 v[58:59], v[128:129], v[62:63], v[58:59]
	v_pk_fma_f32 v[36:37], v[128:129], v[64:65], v[36:37]
	v_pk_fma_f32 v[16:17], v[128:129], v[66:67], v[16:17]
	v_pk_fma_f32 v[170:171], v[132:133], v[62:63], v[170:171]
	v_pk_fma_f32 v[58:59], v[132:133], v[64:65], v[58:59]
	v_pk_fma_f32 v[36:37], v[132:133], v[66:67], v[36:37]
	v_pk_fma_f32 v[16:17], v[132:133], v[68:69], v[16:17]
	v_pk_fma_f32 v[170:171], v[134:135], v[64:65], v[170:171]
	v_pk_fma_f32 v[58:59], v[134:135], v[66:67], v[58:59]
	v_pk_fma_f32 v[36:37], v[134:135], v[68:69], v[36:37]
	v_pk_fma_f32 v[16:17], v[134:135], v[70:71], v[16:17]
	v_pk_fma_f32 v[170:171], v[136:137], v[66:67], v[170:171]
	v_pk_fma_f32 v[58:59], v[136:137], v[68:69], v[58:59]
	v_pk_fma_f32 v[36:37], v[136:137], v[70:71], v[36:37]
	v_pk_fma_f32 v[16:17], v[136:137], v[72:73], v[16:17]
	v_pk_fma_f32 v[170:171], v[142:143], v[68:69], v[170:171]
	v_pk_fma_f32 v[58:59], v[142:143], v[70:71], v[58:59]
	v_pk_fma_f32 v[36:37], v[142:143], v[72:73], v[36:37]
	v_pk_fma_f32 v[16:17], v[142:143], v[74:75], v[16:17]
	v_pk_fma_f32 v[170:171], v[138:139], v[70:71], v[170:171]
	v_pk_fma_f32 v[58:59], v[138:139], v[72:73], v[58:59]
	v_pk_fma_f32 v[36:37], v[138:139], v[74:75], v[36:37]
	v_pk_fma_f32 v[16:17], v[138:139], v[76:77], v[16:17]
	v_pk_fma_f32 v[170:171], v[140:141], v[72:73], v[170:171]
	v_pk_fma_f32 v[58:59], v[140:141], v[74:75], v[58:59]
	v_pk_fma_f32 v[36:37], v[140:141], v[76:77], v[36:37]
	v_pk_fma_f32 v[16:17], v[140:141], v[78:79], v[16:17]
	v_pk_fma_f32 v[170:171], v[144:145], v[74:75], v[170:171]
	v_pk_fma_f32 v[58:59], v[144:145], v[76:77], v[58:59]
	v_pk_fma_f32 v[36:37], v[144:145], v[78:79], v[36:37]
	v_pk_fma_f32 v[16:17], v[144:145], v[194:195], v[16:17]
	ds_write_b32 v172, v170 offset:8192
	ds_write_b32 v178, v171 offset:8192
	ds_write_b32 v172, v58 offset:10240
	ds_write_b32 v178, v59 offset:10240
	ds_write_b32 v172, v36 offset:12288
	ds_write_b32 v178, v37 offset:12288
	ds_write_b32 v172, v16 offset:14336
	ds_write_b32 v178, v17 offset:14336
	s_cbranch_scc1 .LBB0_293
	s_lshl_b64 s[26:27], s[60:61], 16
	v_lshl_add_u64 v[16:17], v[190:191], 0, s[26:27]
	s_mov_b32 s2, 0
	s_waitcnt lgkmcnt(0)
	s_barrier
